# ln_mod loop: all 16 loads per row issued up front in distinct registers (compiler had serialised them into 4 round trips)
# speedup vs baseline: 1.0179x; 1.0039x over previous
.LBB0_380:
	s_or_b64 exec, exec, s[26:27]
	v_and_b32_e32 v13, 0x7e00, v27
	v_and_b32_e32 v12, 0x7e00, v28
	v_lshl_add_u64 v[38:39], v[10:11], 0, v[0:1]
	v_lshlrev_b32_e32 v10, 2, v13
	v_mov_b32_e32 v11, v1
	v_lshl_add_u64 v[40:41], v[4:5], 0, v[10:11]
	v_lshlrev_b32_e32 v10, 2, v12
	v_lshl_add_u64 v[10:11], v[6:7], 0, v[10:11]
	s_mov_b32 s2, 0x1620000
	v_add_co_u32_e32 v42, vcc, s2, v10
	v_addc_co_u32_e32 v43, vcc, 0, v11, vcc
	global_load_dwordx4 v[30:33], v[38:39], off
	global_load_dwordx4 v[34:37], v[40:41], off
	global_load_dwordx4 v[82:85], v[38:39], off offset:1024
	global_load_dwordx4 v[86:89], v[40:41], off offset:1024
	global_load_dwordx4 v[90:93], v[38:39], off offset:2048
	global_load_dwordx4 v[94:97], v[42:43], off
	global_load_dwordx4 v[12:15], v[38:39], off offset:3072
	global_load_dwordx4 v[16:19], v[42:43], off offset:1024
	v_min_i32_e32 v10, 0x8000, v2
	v_ashrrev_i32_e32 v10, 12, v10
	v_mul_i32_i24_e32 v10, 0xc00, v10
	v_readlane_b32 s24, v252, 15
	v_ashrrev_i32_e32 v11, 31, v10
	v_readlane_b32 s25, v252, 16
	s_nop 1
	v_lshl_add_u64 v[10:11], v[10:11], 2, s[24:25]
	v_lshl_add_u64 v[98:99], v[10:11], 0, v[0:1]
	v_lshlrev_b64 v[10:11], 11, v[2:3]
	s_mov_b64 s[24:25], 0x1000
	v_lshl_add_u64 v[100:101], v[98:99], 0, s[24:25]
	v_lshl_add_u64 v[10:11], v[8:9], 0, v[10:11]
	global_load_dwordx4 v[104:107], v[100:101], off offset:1024
	global_load_dwordx4 v[108:111], v[100:101], off offset:2048
	global_load_dwordx4 v[112:115], v[100:101], off
	global_load_dwordx4 v[116:119], v[98:99], off
	global_load_dwordx4 v[120:123], v[98:99], off offset:1024
	global_load_dwordx4 v[124:127], v[100:101], off offset:3072
	global_load_dwordx4 v[128:131], v[98:99], off offset:2048
	global_load_dwordx4 v[132:135], v[98:99], off offset:3072
	s_waitcnt vmcnt(14)
	v_pk_fma_f32 v[22:23], v[20:21], v[36:37], v[32:33] op_sel_hi:[0,1,1]
	v_pk_fma_f32 v[24:25], v[20:21], v[34:35], v[30:31] op_sel_hi:[0,1,1]
	v_add_f32_e32 v3, 0, v24
	v_add_f32_e32 v3, v3, v25
	v_add_f32_e32 v3, v3, v22
	v_add_f32_e32 v3, v3, v23
	s_waitcnt vmcnt(12)
	v_pk_fma_f32 v[58:59], v[20:21], v[88:89], v[84:85] op_sel_hi:[0,1,1]
	v_pk_fma_f32 v[60:61], v[20:21], v[86:87], v[82:83] op_sel_hi:[0,1,1]
	v_add_f32_e32 v3, v3, v60
	v_add_f32_e32 v3, v3, v61
	v_add_f32_e32 v3, v3, v58
	v_add_f32_e32 v3, v3, v59
	s_waitcnt vmcnt(10)
	v_pk_fma_f32 v[64:65], v[20:21], v[94:95], v[90:91] op_sel_hi:[0,1,1]
	v_pk_fma_f32 v[62:63], v[20:21], v[96:97], v[92:93] op_sel_hi:[0,1,1]
	v_add_f32_e32 v3, v3, v64
	v_add_f32_e32 v3, v3, v65
	v_add_f32_e32 v3, v3, v62
	v_add_f32_e32 v3, v3, v63
	s_waitcnt vmcnt(8)
	v_pk_fma_f32 v[12:13], v[20:21], v[16:17], v[12:13] op_sel_hi:[0,1,1]
	v_pk_fma_f32 v[14:15], v[20:21], v[18:19], v[14:15] op_sel_hi:[0,1,1]
	v_add_f32_e32 v3, v3, v12
	v_add_f32_e32 v3, v3, v13
	v_add_f32_e32 v3, v3, v14
	v_add_f32_e32 v3, v3, v15
	s_waitcnt vmcnt(6)
	v_pk_add_f32 v[108:109], v[108:109], 1.0 op_sel_hi:[1,0]
	v_add_f32_dpp v3, v3, v3 quad_perm:[1,0,3,2] row_mask:0xf bank_mask:0xf bound_ctrl:1
	v_pk_add_f32 v[104:105], v[104:105], 1.0 op_sel_hi:[1,0]
	v_pk_add_f32 v[106:107], v[106:107], 1.0 op_sel_hi:[1,0]
	v_add_f32_dpp v3, v3, v3 quad_perm:[2,3,0,1] row_mask:0xf bank_mask:0xf bound_ctrl:1
	v_pk_add_f32 v[110:111], v[110:111], 1.0 op_sel_hi:[1,0]
	s_waitcnt vmcnt(5)
	v_pk_add_f32 v[112:113], v[112:113], 1.0 op_sel_hi:[1,0]
	v_add_f32_dpp v3, v3, v3 row_half_mirror row_mask:0xf bank_mask:0xf bound_ctrl:1
	v_pk_add_f32 v[114:115], v[114:115], 1.0 op_sel_hi:[1,0]
	s_waitcnt vmcnt(2)
	v_pk_add_f32 v[124:125], v[124:125], 1.0 op_sel_hi:[1,0]
	v_add_f32_dpp v3, v3, v3 row_mirror row_mask:0xf bank_mask:0xf bound_ctrl:1
	ds_bpermute_b32 v20, v21, v3
	s_waitcnt lgkmcnt(0)
	v_add_f32_e32 v3, v3, v20
	ds_bpermute_b32 v20, v26, v3
	s_waitcnt lgkmcnt(0)
	v_add_f32_e32 v3, v3, v20
	v_mul_f32_e32 v20, 0x3a800000, v3
	v_pk_add_f32 v[24:25], v[24:25], v[20:21] op_sel_hi:[1,0] neg_lo:[0,1] neg_hi:[0,1]
	v_pk_add_f32 v[22:23], v[22:23], v[20:21] op_sel_hi:[1,0] neg_lo:[0,1] neg_hi:[0,1]
	v_pk_mul_f32 v[66:67], v[24:25], v[24:25]
	v_pk_mul_f32 v[68:69], v[22:23], v[22:23]
	v_add_f32_e32 v3, v66, v67
	v_pk_add_f32 v[60:61], v[60:61], v[20:21] op_sel_hi:[1,0] neg_lo:[0,1] neg_hi:[0,1]
	v_add_f32_e32 v3, v68, v3
	v_pk_mul_f32 v[70:71], v[60:61], v[60:61]
	v_add_f32_e32 v3, v69, v3
	v_pk_add_f32 v[58:59], v[58:59], v[20:21] op_sel_hi:[1,0] neg_lo:[0,1] neg_hi:[0,1]
	v_add_f32_e32 v3, v70, v3
	v_pk_mul_f32 v[72:73], v[58:59], v[58:59]
	v_add_f32_e32 v3, v71, v3
	v_pk_add_f32 v[64:65], v[64:65], v[20:21] op_sel_hi:[1,0] neg_lo:[0,1] neg_hi:[0,1]
	v_add_f32_e32 v3, v72, v3
	v_pk_mul_f32 v[74:75], v[64:65], v[64:65]
	v_add_f32_e32 v3, v73, v3
	v_pk_add_f32 v[62:63], v[62:63], v[20:21] op_sel_hi:[1,0] neg_lo:[0,1] neg_hi:[0,1]
	v_add_f32_e32 v3, v74, v3
	v_pk_mul_f32 v[76:77], v[62:63], v[62:63]
	v_add_f32_e32 v3, v75, v3
	v_pk_add_f32 v[12:13], v[12:13], v[20:21] op_sel_hi:[1,0] neg_lo:[0,1] neg_hi:[0,1]
	v_add_f32_e32 v3, v76, v3
	v_pk_mul_f32 v[80:81], v[12:13], v[12:13]
	v_add_f32_e32 v3, v77, v3
	v_pk_add_f32 v[14:15], v[14:15], v[20:21] op_sel_hi:[1,0] neg_lo:[0,1] neg_hi:[0,1]
	v_add_f32_e32 v3, v80, v3
	v_pk_mul_f32 v[78:79], v[14:15], v[14:15]
	v_add_f32_e32 v3, v81, v3
	v_add_f32_e32 v3, v78, v3
	v_add_f32_e32 v3, v79, v3
	s_nop 1
	v_add_f32_dpp v3, v3, v3 quad_perm:[1,0,3,2] row_mask:0xf bank_mask:0xf bound_ctrl:1
	s_nop 1
	v_add_f32_dpp v3, v3, v3 quad_perm:[2,3,0,1] row_mask:0xf bank_mask:0xf bound_ctrl:1
	s_nop 1
	v_add_f32_dpp v3, v3, v3 row_half_mirror row_mask:0xf bank_mask:0xf bound_ctrl:1
	s_nop 1
	v_add_f32_dpp v3, v3, v3 row_mirror row_mask:0xf bank_mask:0xf bound_ctrl:1
	ds_bpermute_b32 v20, v21, v3
	s_waitcnt lgkmcnt(0)
	v_add_f32_e32 v3, v3, v20
	ds_bpermute_b32 v20, v26, v3
	s_waitcnt lgkmcnt(0)
	v_add_f32_e32 v3, v3, v20
	v_fmamk_f32 v3, v3, 0x3a800000, v230
	v_mul_f32_e32 v20, 0x4b800000, v3
	v_cmp_gt_f32_e32 vcc, s72, v3
	s_nop 1
	v_cndmask_b32_e32 v3, v3, v20, vcc
	v_rsq_f32_e32 v3, v3
	s_nop 0
	v_mul_f32_e32 v20, 0x45800000, v3
	v_cndmask_b32_e32 v20, v3, v20, vcc
	v_pk_mul_f32 v[24:25], v[24:25], v[20:21] op_sel_hi:[1,0]
	v_pk_mul_f32 v[22:23], v[22:23], v[20:21] op_sel_hi:[1,0]
	v_pk_fma_f32 v[24:25], v[112:113], v[24:25], v[116:117]
	v_pk_fma_f32 v[22:23], v[114:115], v[22:23], v[118:119]
	v_cvt_pk_bf16_f32 v24, v24, v25
	v_cvt_pk_bf16_f32 v25, v22, v23
	global_store_dwordx2 v[10:11], v[24:25], off
	v_pk_mul_f32 v[22:23], v[60:61], v[20:21] op_sel_hi:[1,0]
	v_pk_mul_f32 v[24:25], v[58:59], v[20:21] op_sel_hi:[1,0]
	v_pk_fma_f32 v[22:23], v[104:105], v[22:23], v[120:121]
	v_pk_fma_f32 v[24:25], v[106:107], v[24:25], v[122:123]
	v_cvt_pk_bf16_f32 v22, v22, v23
	v_cvt_pk_bf16_f32 v23, v24, v25
	v_pk_mul_f32 v[12:13], v[12:13], v[20:21] op_sel_hi:[1,0]
	v_readlane_b32 s2, v251, 19
	global_store_dwordx2 v[10:11], v[22:23], off offset:512
	v_pk_mul_f32 v[22:23], v[64:65], v[20:21] op_sel_hi:[1,0]
	v_pk_mul_f32 v[24:25], v[62:63], v[20:21] op_sel_hi:[1,0]
	s_waitcnt vmcnt(2)
	v_pk_fma_f32 v[12:13], v[12:13], v[124:125], v[132:133]
	v_pk_mul_f32 v[14:15], v[14:15], v[20:21] op_sel_hi:[1,0]
	v_pk_add_f32 v[132:133], v[126:127], 1.0 op_sel_hi:[1,0]
	v_add_u32_e32 v2, s2, v2
	s_mov_b32 s2, 0x87ff
	v_pk_fma_f32 v[22:23], v[108:109], v[22:23], v[128:129]
	v_pk_fma_f32 v[24:25], v[110:111], v[24:25], v[130:131]
	v_pk_fma_f32 v[14:15], v[14:15], v[132:133], v[134:135]
	v_cmp_lt_i32_e32 vcc, s2, v2
	v_readlane_b32 s2, v253, 56
	v_cvt_pk_bf16_f32 v22, v22, v23
	v_cvt_pk_bf16_f32 v23, v24, v25
	v_cvt_pk_bf16_f32 v12, v12, v13
	v_cvt_pk_bf16_f32 v13, v14, v15
	v_add_u32_e32 v27, s41, v27
	s_or_b64 s[22:23], vcc, s[22:23]
	v_add_u32_e32 v28, s2, v28
	global_store_dwordx2 v[10:11], v[22:23], off offset:1024
	global_store_dwordx2 v[10:11], v[12:13], off offset:1536
	s_andn2_b64 exec, exec, s[22:23]
	s_cbranch_execz .LBB0_385
